# attention Y segments: one counted lgkmcnt per 4-MFMA group, matched placement of the FFN-F2 code
# speedup vs baseline: 1.0080x; 1.0021x over previous
.LBB0_622:
	v_add3_u32 v165, s57, v143, v163
	ds_read_b128 v[190:193], v165 offset:18432
	ds_read_b128 v[194:197], v165 offset:18448
	ds_read_b128 v[128:131], v165 offset:23040
	ds_read_b128 v[132:135], v165 offset:23056
	ds_read_b128 v[136:139], v165 offset:27648
	ds_read_b128 v[166:169], v165 offset:27664
	ds_read_b128 v[170:173], v165 offset:32256
	ds_read_b128 v[178:181], v165 offset:32272
	v_exp_f32_e32 v96, v96
	v_exp_f32_e32 v97, v97
	v_exp_f32_e32 v98, v98
	v_exp_f32_e32 v99, v99
	v_exp_f32_e32 v100, v100
	v_add_f32_e32 v198, v97, v96
	v_exp_f32_e32 v101, v101
	v_add_f32_e32 v198, v98, v198
	v_exp_f32_e32 v102, v102
	v_add_f32_e32 v198, v99, v198
	v_exp_f32_e32 v103, v103
	v_add_f32_e32 v198, v100, v198
	v_exp_f32_e32 v104, v104
	v_add_f32_e32 v198, v101, v198
	v_exp_f32_e32 v105, v105
	v_add_f32_e32 v198, v102, v198
	v_exp_f32_e32 v106, v106
	v_add_f32_e32 v198, v103, v198
	v_exp_f32_e32 v107, v107
	v_add_f32_e32 v198, v104, v198
	v_exp_f32_e32 v108, v108
	v_add_f32_e32 v198, v105, v198
	v_exp_f32_e32 v109, v109
	v_add_f32_e32 v198, v106, v198
	v_exp_f32_e32 v110, v110
	v_add_f32_e32 v198, v107, v198
	v_exp_f32_e32 v111, v111
	v_add_f32_e32 v198, v108, v198
	v_add_f32_e32 v198, v109, v198
	v_add_f32_e32 v198, v110, v198
	v_add_f32_e32 v198, v111, v198
	v_add_f32_e32 v157, v157, v198
	v_cvt_pk_bf16_f32 v96, v96, v97
	v_cvt_pk_bf16_f32 v97, v98, v99
	v_cvt_pk_bf16_f32 v98, v100, v101
	v_cvt_pk_bf16_f32 v99, v102, v103
	v_cvt_pk_bf16_f32 v100, v104, v105
	v_cvt_pk_bf16_f32 v101, v106, v107
	v_cvt_pk_bf16_f32 v102, v108, v109
	v_cvt_pk_bf16_f32 v103, v110, v111
	s_waitcnt lgkmcnt(4)
	v_mfma_f32_32x32x16_bf16 v[48:63], v[190:193], v[96:99], v[48:63]
	v_exp_f32_e32 v174, v80
	v_exp_f32_e32 v175, v81
	v_exp_f32_e32 v182, v82
	v_exp_f32_e32 v183, v83
	v_add_f32_e32 v80, v175, v174
	v_add_f32_e32 v80, v182, v80
	v_mfma_f32_32x32x16_bf16 v[0:15], v[128:131], v[96:99], v[0:15]
	v_add_f32_e32 v80, v183, v80
	v_mfma_f32_32x32x16_bf16 v[48:63], v[194:197], v[100:103], v[48:63]
	v_exp_f32_e32 v128, v84
	v_exp_f32_e32 v129, v85
	v_exp_f32_e32 v130, v86
	v_exp_f32_e32 v131, v87
	v_add_f32_e32 v80, v128, v80
	v_add_f32_e32 v80, v129, v80
	v_add_f32_e32 v80, v130, v80
	v_mfma_f32_32x32x16_bf16 v[0:15], v[132:135], v[100:103], v[0:15]
	v_add_f32_e32 v184, v131, v80
	ds_read_b128 v[80:83], v165 offset:18496
	ds_read_b128 v[84:87], v165 offset:18512
	ds_read_b128 v[104:107], v165 offset:23104
	ds_read_b128 v[108:111], v165 offset:23120
	s_waitcnt lgkmcnt(4)
	v_mfma_f32_32x32x16_bf16 v[32:47], v[136:139], v[96:99], v[32:47]
	v_exp_f32_e32 v132, v88
	v_exp_f32_e32 v133, v89
	v_exp_f32_e32 v134, v90
	v_exp_f32_e32 v135, v91
	v_add_f32_e32 v88, v132, v184
	v_add_f32_e32 v88, v133, v88
	v_add_f32_e32 v88, v134, v88
	v_mfma_f32_32x32x16_bf16 v[16:31], v[170:173], v[96:99], v[16:31]
	v_add_f32_e32 v88, v135, v88
	v_exp_f32_e32 v96, v92
	v_mfma_f32_32x32x16_bf16 v[32:47], v[166:169], v[100:103], v[32:47]
	v_exp_f32_e32 v97, v93
	v_exp_f32_e32 v98, v94
	v_exp_f32_e32 v95, v95
	v_add_f32_e32 v88, v96, v88
	v_add_f32_e32 v88, v97, v88
	v_add_f32_e32 v88, v98, v88
	v_add_f32_e32 v88, v95, v88
	v_mfma_f32_32x32x16_bf16 v[16:31], v[178:181], v[100:103], v[16:31]
	v_add_f32_e32 v157, v157, v88
	v_cvt_pk_bf16_f32 v88, v174, v175
	v_cvt_pk_bf16_f32 v89, v182, v183
	v_cvt_pk_bf16_f32 v90, v128, v129
	v_cvt_pk_bf16_f32 v91, v130, v131
	v_cvt_pk_bf16_f32 v92, v132, v133
	v_cvt_pk_bf16_f32 v93, v134, v135
	v_cvt_pk_bf16_f32 v94, v96, v97
	v_cvt_pk_bf16_f32 v95, v98, v95
	ds_read_b128 v[96:99], v165 offset:27712
	ds_read_b128 v[100:103], v165 offset:27728
	ds_read_b128 v[128:131], v165 offset:32320
	ds_read_b128 v[132:135], v165 offset:32336
	s_waitcnt lgkmcnt(4)
	v_mfma_f32_32x32x16_bf16 v[48:63], v[80:83], v[88:91], v[48:63]
	v_mfma_f32_32x32x16_bf16 v[0:15], v[104:107], v[88:91], v[0:15]
	s_add_i32 s4, s9, 0x9000
	s_cmp_lg_u32 s9, 0x12000
	s_cselect_b32 s9, s4, 0
	v_mfma_f32_32x32x16_bf16 v[48:63], v[84:87], v[92:95], v[48:63]
	v_mfma_f32_32x32x16_bf16 v[0:15], v[108:111], v[92:95], v[0:15]
	s_add_i32 s4, s56, 1
	s_cmp_lg_u32 s56, 2
	s_cselect_b32 s56, s4, 0
	s_add_i32 s8, s8, 1
	s_add_i32 s87, s87, 64
	s_cmpk_lg_i32 s87, 0xfc0
	s_waitcnt lgkmcnt(0)
	s_barrier
	s_cbranch_scc0 .Lv1p_flush
	s_add_i32 s57, s9, 0
	s_add_i32 s4, s57, s94
	v_add_u32_e32 v80, s4, v162
	v_add_u32_e32 v84, v80, v146
	ds_read_b128 v[80:83], v84
	ds_read_b128 v[220:223], v84 offset:32
	ds_read_b128 v[136:139], v84 offset:4608
	ds_read_b128 v[224:227], v84 offset:4640
	ds_read_b128 v[166:169], v84 offset:64
	ds_read_b128 v[170:173], v84 offset:96
	ds_read_b128 v[178:181], v84 offset:4672
	ds_read_b128 v[182:185], v84 offset:4704
	v_mfma_f32_32x32x16_bf16 v[32:47], v[96:99], v[88:91], v[32:47]
	v_mfma_f32_32x32x16_bf16 v[16:31], v[128:131], v[88:91], v[16:31]
	v_mfma_f32_32x32x16_bf16 v[32:47], v[100:103], v[92:95], v[32:47]
	v_mfma_f32_32x32x16_bf16 v[16:31], v[132:135], v[92:95], v[16:31]
	s_branch .Lv1p_body

.LBB0_643:
	v_add_u32_e32 v128, s50, v164
	s_waitcnt lgkmcnt(0)
	s_barrier
	v_add_u32_e32 v168, v128, v165
	ds_read_b128 v[140:143], v168 offset:18432
	ds_read_b128 v[132:135], v168 offset:18448
	ds_read_b128 v[136:139], v168 offset:23040
	ds_read_b128 v[128:131], v168 offset:23056
	ds_read_b128 v[178:181], v168 offset:27648
	ds_read_b128 v[182:185], v168 offset:27664
	ds_read_b128 v[186:189], v168 offset:32256
	ds_read_b128 v[190:193], v168 offset:32272
	v_exp_f32_e32 v96, v96
	v_exp_f32_e32 v97, v97
	v_exp_f32_e32 v98, v98
	v_exp_f32_e32 v99, v99
	v_exp_f32_e32 v100, v100
	v_exp_f32_e32 v101, v101
	v_exp_f32_e32 v102, v102
	v_exp_f32_e32 v103, v103
	v_exp_f32_e32 v104, v104
	v_exp_f32_e32 v105, v105
	v_exp_f32_e32 v106, v106
	v_exp_f32_e32 v107, v107
	v_exp_f32_e32 v108, v108
	v_exp_f32_e32 v109, v109
	v_exp_f32_e32 v110, v110
	v_exp_f32_e32 v111, v111
	v_cvt_pk_bf16_f32 v170, v96, v97
	v_cvt_pk_bf16_f32 v171, v98, v99
	v_cvt_pk_bf16_f32 v172, v100, v101
	v_cvt_pk_bf16_f32 v173, v102, v103
	v_cvt_pk_bf16_f32 v194, v104, v105
	v_cvt_pk_bf16_f32 v195, v106, v107
	v_cvt_pk_bf16_f32 v196, v108, v109
	v_cvt_pk_bf16_f32 v197, v110, v111
	s_waitcnt lgkmcnt(4)
	v_mfma_f32_32x32x16_bf16 v[48:63], v[140:143], v[170:173], v[48:63]
	v_exp_f32_e32 v80, v80
	v_exp_f32_e32 v81, v81
	v_exp_f32_e32 v82, v82
	v_exp_f32_e32 v83, v83
	v_mfma_f32_32x32x16_bf16 v[0:15], v[136:139], v[170:173], v[0:15]
	v_mfma_f32_32x32x16_bf16 v[48:63], v[132:135], v[194:197], v[48:63]
	v_exp_f32_e32 v84, v84
	v_exp_f32_e32 v85, v85
	v_exp_f32_e32 v86, v86
	v_exp_f32_e32 v87, v87
	v_mfma_f32_32x32x16_bf16 v[0:15], v[128:131], v[194:197], v[0:15]
	ds_read_b128 v[128:131], v168 offset:18496
	ds_read_b128 v[132:135], v168 offset:18512
	ds_read_b128 v[136:139], v168 offset:23104
	ds_read_b128 v[140:143], v168 offset:23120
	s_waitcnt lgkmcnt(4)
	v_mfma_f32_32x32x16_bf16 v[32:47], v[178:181], v[170:173], v[32:47]
	v_exp_f32_e32 v88, v88
	v_exp_f32_e32 v89, v89
	v_exp_f32_e32 v90, v90
	v_exp_f32_e32 v91, v91
	v_mfma_f32_32x32x16_bf16 v[16:31], v[186:189], v[170:173], v[16:31]
	v_mfma_f32_32x32x16_bf16 v[32:47], v[182:185], v[194:197], v[32:47]
	v_exp_f32_e32 v92, v92
	v_exp_f32_e32 v93, v93
	v_exp_f32_e32 v94, v94
	v_exp_f32_e32 v95, v95
	v_cvt_pk_bf16_f32 v170, v80, v81
	v_cvt_pk_bf16_f32 v171, v82, v83
	v_cvt_pk_bf16_f32 v172, v84, v85
	v_mfma_f32_32x32x16_bf16 v[16:31], v[190:193], v[194:197], v[16:31]
	v_cvt_pk_bf16_f32 v173, v86, v87
	v_cvt_pk_bf16_f32 v178, v88, v89
	v_cvt_pk_bf16_f32 v179, v90, v91
	v_cvt_pk_bf16_f32 v180, v92, v93
	v_cvt_pk_bf16_f32 v181, v94, v95
	ds_read_b128 v[182:185], v168 offset:27712
	ds_read_b128 v[186:189], v168 offset:27728
	ds_read_b128 v[190:193], v168 offset:32320
	ds_read_b128 v[194:197], v168 offset:32336
	s_cmp_gt_u32 s33, 61
	s_cselect_b64 s[50:51], -1, 0
	s_and_b64 vcc, exec, s[50:51]
	s_cbranch_vccnz .LBB0_645
	s_mul_i32 s63, s45, 0x9000
	s_or_b32 m0, s63, s35
	s_nop 0
	global_load_lds_dwordx4 v[240:241], off
	s_add_i32 m0, s2, s63
	v_lshl_add_u64 v[240:241], v[240:241], 0, v[200:201]
	global_load_lds_dwordx4 v[242:243], off
	s_add_i32 m0, s63, s21
	v_lshl_add_u64 v[242:243], v[242:243], 0, v[202:203]
	global_load_lds_dwordx4 v[244:245], off
	s_add_i32 m0, s26, s63
	v_lshl_add_u64 v[244:245], v[244:245], 0, v[204:205]
	global_load_lds_dwordx4 v[246:247], off
	s_add_i32 m0, s63, s3
	v_lshl_add_u64 v[246:247], v[246:247], 0, v[206:207]
	global_load_lds_dwordx4 v[248:249], off
	v_lshl_add_u64 v[248:249], v[248:249], 0, v[208:209]
.LBB0_645:
	s_waitcnt lgkmcnt(4)
	v_mfma_f32_32x32x16_bf16 v[48:63], v[128:131], v[170:173], v[48:63]
	v_add_f32_e32 v80, v81, v80
	v_add_f32_e32 v80, v82, v80
	v_add_f32_e32 v80, v83, v80
	v_add_f32_e32 v80, v84, v80
	v_mfma_f32_32x32x16_bf16 v[0:15], v[136:139], v[170:173], v[0:15]
	v_add_f32_e32 v80, v85, v80
	v_add_f32_e32 v80, v86, v80
	v_add_f32_e32 v80, v87, v80
	v_add_f32_e32 v80, v88, v80
	s_add_i32 s4, s44, 0x9000
	s_cmp_lg_u32 s44, 0x12000
	s_cselect_b32 s44, s4, 0
	s_add_i32 s4, s45, 1
	v_mfma_f32_32x32x16_bf16 v[48:63], v[132:135], v[178:181], v[48:63]
	v_add_f32_e32 v80, v89, v80
	v_add_f32_e32 v80, v90, v80
	v_add_f32_e32 v80, v91, v80
	v_add_f32_e32 v80, v92, v80
	v_mfma_f32_32x32x16_bf16 v[0:15], v[140:143], v[178:181], v[0:15]
	v_add_f32_e32 v80, v93, v80
	v_add_f32_e32 v80, v94, v80
	v_add_f32_e32 v251, v95, v80
	s_cmp_lg_u32 s45, 2
	s_cselect_b32 s45, s4, 0
	s_add_i32 s33, s33, 1
	s_add_u32 s10, s10, 0x60000
	s_addc_u32 s11, s11, 0
	s_add_i32 s20, s20, 64
	s_mov_b64 s[60:61], -1
	s_and_b64 vcc, exec, s[50:51]
	s_cbranch_vccz .LBB0_647
	s_waitcnt vmcnt(0) lgkmcnt(0)
	s_barrier
	s_mov_b64 s[60:61], 0

.LBB0_683:
	v_add3_u32 v165, s57, v143, v163
	ds_read_b128 v[190:193], v165 offset:18432
	ds_read_b128 v[194:197], v165 offset:18448
	ds_read_b128 v[128:131], v165 offset:23040
	ds_read_b128 v[132:135], v165 offset:23056
	ds_read_b128 v[136:139], v165 offset:27648
	ds_read_b128 v[166:169], v165 offset:27664
	ds_read_b128 v[170:173], v165 offset:32256
	ds_read_b128 v[178:181], v165 offset:32272
	v_exp_f32_e32 v96, v96
	v_exp_f32_e32 v97, v97
	v_exp_f32_e32 v98, v98
	v_exp_f32_e32 v99, v99
	v_exp_f32_e32 v100, v100
	v_add_f32_e32 v198, v97, v96
	v_exp_f32_e32 v101, v101
	v_add_f32_e32 v198, v98, v198
	v_exp_f32_e32 v102, v102
	v_add_f32_e32 v198, v99, v198
	v_exp_f32_e32 v103, v103
	v_add_f32_e32 v198, v100, v198
	v_exp_f32_e32 v104, v104
	v_add_f32_e32 v198, v101, v198
	v_exp_f32_e32 v105, v105
	v_add_f32_e32 v198, v102, v198
	v_exp_f32_e32 v106, v106
	v_add_f32_e32 v198, v103, v198
	v_exp_f32_e32 v107, v107
	v_add_f32_e32 v198, v104, v198
	v_exp_f32_e32 v108, v108
	v_add_f32_e32 v198, v105, v198
	v_exp_f32_e32 v109, v109
	v_add_f32_e32 v198, v106, v198
	v_exp_f32_e32 v110, v110
	v_add_f32_e32 v198, v107, v198
	v_exp_f32_e32 v111, v111
	v_add_f32_e32 v198, v108, v198
	v_add_f32_e32 v198, v109, v198
	v_add_f32_e32 v198, v110, v198
	v_add_f32_e32 v198, v111, v198
	v_add_f32_e32 v157, v157, v198
	v_cvt_pk_bf16_f32 v96, v96, v97
	v_cvt_pk_bf16_f32 v97, v98, v99
	v_cvt_pk_bf16_f32 v98, v100, v101
	v_cvt_pk_bf16_f32 v99, v102, v103
	v_cvt_pk_bf16_f32 v100, v104, v105
	v_cvt_pk_bf16_f32 v101, v106, v107
	v_cvt_pk_bf16_f32 v102, v108, v109
	v_cvt_pk_bf16_f32 v103, v110, v111
	s_waitcnt lgkmcnt(4)
	v_mfma_f32_32x32x16_bf16 v[48:63], v[190:193], v[96:99], v[48:63]
	v_exp_f32_e32 v174, v80
	v_exp_f32_e32 v175, v81
	v_exp_f32_e32 v182, v82
	v_exp_f32_e32 v183, v83
	v_add_f32_e32 v80, v175, v174
	v_add_f32_e32 v80, v182, v80
	v_mfma_f32_32x32x16_bf16 v[0:15], v[128:131], v[96:99], v[0:15]
	v_add_f32_e32 v80, v183, v80
	v_mfma_f32_32x32x16_bf16 v[48:63], v[194:197], v[100:103], v[48:63]
	v_exp_f32_e32 v128, v84
	v_exp_f32_e32 v129, v85
	v_exp_f32_e32 v130, v86
	v_exp_f32_e32 v131, v87
	v_add_f32_e32 v80, v128, v80
	v_add_f32_e32 v80, v129, v80
	v_add_f32_e32 v80, v130, v80
	v_mfma_f32_32x32x16_bf16 v[0:15], v[132:135], v[100:103], v[0:15]
	v_add_f32_e32 v184, v131, v80
	ds_read_b128 v[80:83], v165 offset:18496
	ds_read_b128 v[84:87], v165 offset:18512
	ds_read_b128 v[104:107], v165 offset:23104
	ds_read_b128 v[108:111], v165 offset:23120
	s_waitcnt lgkmcnt(4)
	v_mfma_f32_32x32x16_bf16 v[32:47], v[136:139], v[96:99], v[32:47]
	v_exp_f32_e32 v132, v88
	v_exp_f32_e32 v133, v89
	v_exp_f32_e32 v134, v90
	v_exp_f32_e32 v135, v91
	v_add_f32_e32 v88, v132, v184
	v_add_f32_e32 v88, v133, v88
	v_add_f32_e32 v88, v134, v88
	v_mfma_f32_32x32x16_bf16 v[16:31], v[170:173], v[96:99], v[16:31]
	v_add_f32_e32 v88, v135, v88
	v_exp_f32_e32 v96, v92
	v_mfma_f32_32x32x16_bf16 v[32:47], v[166:169], v[100:103], v[32:47]
	v_exp_f32_e32 v97, v93
	v_exp_f32_e32 v98, v94
	v_exp_f32_e32 v95, v95
	v_add_f32_e32 v88, v96, v88
	v_add_f32_e32 v88, v97, v88
	v_add_f32_e32 v88, v98, v88
	v_add_f32_e32 v88, v95, v88
	v_mfma_f32_32x32x16_bf16 v[16:31], v[178:181], v[100:103], v[16:31]
	v_add_f32_e32 v157, v157, v88
	v_cvt_pk_bf16_f32 v88, v174, v175
	v_cvt_pk_bf16_f32 v89, v182, v183
	v_cvt_pk_bf16_f32 v90, v128, v129
	v_cvt_pk_bf16_f32 v91, v130, v131
	v_cvt_pk_bf16_f32 v92, v132, v133
	v_cvt_pk_bf16_f32 v93, v134, v135
	v_cvt_pk_bf16_f32 v94, v96, v97
	v_cvt_pk_bf16_f32 v95, v98, v95
	ds_read_b128 v[96:99], v165 offset:27712
	ds_read_b128 v[100:103], v165 offset:27728
	ds_read_b128 v[128:131], v165 offset:32320
	ds_read_b128 v[132:135], v165 offset:32336
	s_waitcnt lgkmcnt(4)
	v_mfma_f32_32x32x16_bf16 v[48:63], v[80:83], v[88:91], v[48:63]
	v_mfma_f32_32x32x16_bf16 v[0:15], v[104:107], v[88:91], v[0:15]
	s_add_i32 s4, s9, 0x9000
	s_cmp_lg_u32 s9, 0x12000
	s_cselect_b32 s9, s4, 0
	s_add_i32 s4, s56, 1
	v_mfma_f32_32x32x16_bf16 v[48:63], v[84:87], v[92:95], v[48:63]
	v_mfma_f32_32x32x16_bf16 v[0:15], v[108:111], v[92:95], v[0:15]
	s_cmp_lg_u32 s56, 2
	s_cselect_b32 s56, s4, 0
	s_add_i32 s8, s8, 1
	s_add_u32 s10, s10, 0x60000
	s_addc_u32 s11, s11, 0
	s_add_i32 s58, s58, 64
	s_cmpk_lg_i32 s58, 0x7c0
	s_waitcnt lgkmcnt(0)
	s_barrier
	s_cbranch_scc0 .Lv1s_flush
	s_add_i32 s57, s9, 0
	s_add_i32 s4, s57, s94
	v_add_u32_e32 v80, s4, v162
	v_add_u32_e32 v84, v80, v146
	ds_read_b128 v[80:83], v84
	ds_read_b128 v[220:223], v84 offset:32
	ds_read_b128 v[136:139], v84 offset:4608
	ds_read_b128 v[224:227], v84 offset:4640
	ds_read_b128 v[166:169], v84 offset:64
	ds_read_b128 v[170:173], v84 offset:96
	ds_read_b128 v[178:181], v84 offset:4672
	ds_read_b128 v[182:185], v84 offset:4704
	v_mfma_f32_32x32x16_bf16 v[32:47], v[96:99], v[88:91], v[32:47]
	v_mfma_f32_32x32x16_bf16 v[16:31], v[128:131], v[88:91], v[16:31]
	v_mfma_f32_32x32x16_bf16 v[32:47], v[100:103], v[92:95], v[32:47]
	v_mfma_f32_32x32x16_bf16 v[16:31], v[132:135], v[92:95], v[16:31]
	s_branch .Lv1s_body

.LBB0_704:
	v_add_u32_e32 v128, s56, v164
	s_waitcnt lgkmcnt(0)
	s_barrier
	v_add_u32_e32 v168, v128, v165
	ds_read_b128 v[140:143], v168 offset:18432
	ds_read_b128 v[132:135], v168 offset:18448
	ds_read_b128 v[136:139], v168 offset:23040
	ds_read_b128 v[128:131], v168 offset:23056
	ds_read_b128 v[178:181], v168 offset:27648
	ds_read_b128 v[182:185], v168 offset:27664
	ds_read_b128 v[186:189], v168 offset:32256
	ds_read_b128 v[190:193], v168 offset:32272
	v_exp_f32_e32 v96, v96
	v_exp_f32_e32 v97, v97
	v_exp_f32_e32 v98, v98
	v_exp_f32_e32 v99, v99
	v_exp_f32_e32 v100, v100
	v_exp_f32_e32 v101, v101
	v_exp_f32_e32 v102, v102
	v_exp_f32_e32 v103, v103
	v_exp_f32_e32 v104, v104
	v_exp_f32_e32 v105, v105
	v_exp_f32_e32 v106, v106
	v_exp_f32_e32 v107, v107
	v_exp_f32_e32 v108, v108
	v_exp_f32_e32 v109, v109
	v_exp_f32_e32 v110, v110
	v_exp_f32_e32 v111, v111
	v_cvt_pk_bf16_f32 v170, v96, v97
	v_cvt_pk_bf16_f32 v171, v98, v99
	v_cvt_pk_bf16_f32 v172, v100, v101
	v_cvt_pk_bf16_f32 v173, v102, v103
	v_cvt_pk_bf16_f32 v194, v104, v105
	v_cvt_pk_bf16_f32 v195, v106, v107
	v_cvt_pk_bf16_f32 v196, v108, v109
	v_cvt_pk_bf16_f32 v197, v110, v111
	s_waitcnt lgkmcnt(4)
	v_mfma_f32_32x32x16_bf16 v[48:63], v[140:143], v[170:173], v[48:63]
	v_exp_f32_e32 v80, v80
	v_exp_f32_e32 v81, v81
	v_exp_f32_e32 v82, v82
	v_exp_f32_e32 v83, v83
	v_mfma_f32_32x32x16_bf16 v[0:15], v[136:139], v[170:173], v[0:15]
	v_mfma_f32_32x32x16_bf16 v[48:63], v[132:135], v[194:197], v[48:63]
	v_exp_f32_e32 v84, v84
	v_exp_f32_e32 v85, v85
	v_exp_f32_e32 v86, v86
	v_exp_f32_e32 v87, v87
	v_mfma_f32_32x32x16_bf16 v[0:15], v[128:131], v[194:197], v[0:15]
	ds_read_b128 v[128:131], v168 offset:18496
	ds_read_b128 v[132:135], v168 offset:18512
	ds_read_b128 v[136:139], v168 offset:23104
	ds_read_b128 v[140:143], v168 offset:23120
	s_waitcnt lgkmcnt(4)
	v_mfma_f32_32x32x16_bf16 v[32:47], v[178:181], v[170:173], v[32:47]
	v_exp_f32_e32 v88, v88
	v_exp_f32_e32 v89, v89
	v_exp_f32_e32 v90, v90
	v_exp_f32_e32 v91, v91
	v_mfma_f32_32x32x16_bf16 v[16:31], v[186:189], v[170:173], v[16:31]
	v_mfma_f32_32x32x16_bf16 v[32:47], v[182:185], v[194:197], v[32:47]
	v_exp_f32_e32 v92, v92
	v_exp_f32_e32 v93, v93
	v_exp_f32_e32 v94, v94
	v_exp_f32_e32 v95, v95
	v_cvt_pk_bf16_f32 v170, v80, v81
	v_cvt_pk_bf16_f32 v171, v82, v83
	v_cvt_pk_bf16_f32 v172, v84, v85
	v_mfma_f32_32x32x16_bf16 v[16:31], v[190:193], v[194:197], v[16:31]
	v_cvt_pk_bf16_f32 v173, v86, v87
	v_cvt_pk_bf16_f32 v178, v88, v89
	v_cvt_pk_bf16_f32 v179, v90, v91
	v_cvt_pk_bf16_f32 v180, v92, v93
	v_cvt_pk_bf16_f32 v181, v94, v95
	ds_read_b128 v[182:185], v168 offset:27712
	ds_read_b128 v[186:189], v168 offset:27728
	ds_read_b128 v[190:193], v168 offset:32320
	ds_read_b128 v[194:197], v168 offset:32336
	s_cmp_gt_u32 s33, 29
	s_cselect_b64 s[60:61], -1, 0
	s_and_b64 vcc, exec, s[60:61]
	s_cbranch_vccnz .LBB0_706
	s_mul_i32 s62, s45, 0x9000
	s_or_b32 m0, s62, s35
	s_nop 0
	global_load_lds_dwordx4 v[240:241], off
	s_add_i32 m0, s2, s62
	v_lshl_add_u64 v[240:241], v[240:241], 0, v[200:201]
	global_load_lds_dwordx4 v[242:243], off
	s_add_i32 m0, s62, s21
	v_lshl_add_u64 v[242:243], v[242:243], 0, v[202:203]
	global_load_lds_dwordx4 v[244:245], off
	s_add_i32 m0, s26, s62
	v_lshl_add_u64 v[244:245], v[244:245], 0, v[204:205]
	global_load_lds_dwordx4 v[246:247], off
	s_add_i32 m0, s62, s3
	v_lshl_add_u64 v[246:247], v[246:247], 0, v[206:207]
	global_load_lds_dwordx4 v[248:249], off
	v_lshl_add_u64 v[248:249], v[248:249], 0, v[208:209]
.LBB0_706:
	s_waitcnt lgkmcnt(4)
	v_mfma_f32_32x32x16_bf16 v[48:63], v[128:131], v[170:173], v[48:63]
	v_add_f32_e32 v80, v81, v80
	v_add_f32_e32 v80, v82, v80
	v_add_f32_e32 v80, v83, v80
	v_add_f32_e32 v80, v84, v80
	v_mfma_f32_32x32x16_bf16 v[0:15], v[136:139], v[170:173], v[0:15]
	v_add_f32_e32 v80, v85, v80
	v_add_f32_e32 v80, v86, v80
	v_add_f32_e32 v80, v87, v80
	v_add_f32_e32 v80, v88, v80
	s_add_i32 s4, s44, 0x9000
	s_cmp_lg_u32 s44, 0x12000
	s_cselect_b32 s44, s4, 0
	v_mfma_f32_32x32x16_bf16 v[48:63], v[132:135], v[178:181], v[48:63]
	v_add_f32_e32 v80, v89, v80
	v_add_f32_e32 v80, v90, v80
	v_add_f32_e32 v80, v91, v80
	v_add_f32_e32 v80, v92, v80
	v_mfma_f32_32x32x16_bf16 v[0:15], v[140:143], v[178:181], v[0:15]
	v_add_f32_e32 v80, v93, v80
	v_add_f32_e32 v80, v94, v80
	v_add_f32_e32 v251, v95, v80
	s_add_i32 s4, s45, 1
	s_cmp_lg_u32 s45, 2
	s_cselect_b32 s45, s4, 0
	s_add_i32 s33, s33, 1
	s_add_i32 s20, s20, 64
	s_mov_b64 s[62:63], -1
	s_and_b64 vcc, exec, s[60:61]
	s_cbranch_vccz .LBB0_708
	s_waitcnt vmcnt(0) lgkmcnt(0)
	s_barrier
	s_mov_b64 s[62:63], 0
